# MLA: V fragments of key-half 1 requested during the PV MFMAs of half 0 (LDS latency hidden); otherwise as previous version
# speedup vs baseline: 1.0157x; 1.0052x over previous
; template <int DQK, bool MASK, int NQ>
; __device__ __forceinline__ void attn_unit(unsigned char* lds, const bf16_t* Qg, int ldq, const bf16_t* Kg, int ldk, const bf16_t* Vtg, bf16_t* Og, int ldo,
;                                           int qi0, int a0, int n1, int b0, int n2, float m0, bool sink) {
;     ...
;               for (int k2 = 0; k2 < 2; ++k2) {
; #pragma unroll
;                   for (int c = 0; c < NC; ++c) {
;                       const bf16x8 kf = *(const bf16x8*)(kb_ + c * 4096 + k2 * 256);
; #pragma unroll
;                       for (int qb = 0; qb < NQ; ++qb) sc[k2][qb] = __builtin_amdgcn_mfma_f32_16x16x32_bf16(kf, qf[qb][c], c == 0 ? negm[qb] : sc[k2][qb], 0, 0, 0);
;                   } }
;               __builtin_amdgcn_s_setprio(0); }
;             if (MASK) { if (kt >= 4) { int dl = kt * 64 + hb * 32 + g * 4 - qw0 - ql; asm volatile("" : "+v"(dl));
; #pragma unroll
;                 for (int k2 = 0; k2 < 2; ++k2)
; #pragma unroll
;                     for (int qb = 0; qb < NQ; ++qb)
; #pragma unroll
;                         for (int j = 0; j < 4; ++j) { const int d = dl + (k2 * 16 + j - qb * 16); if (d > 128 || d < -128) sc[k2][qb][j] = -1e30f; } } }
;             float am = fmaxf(fmaxf(sc[0][0][0], sc[0][0][1]), sc[0][0][2]); am = fmaxf(fmaxf(am, sc[0][0][3]), sc[1][0][0]); am = fmaxf(fmaxf(am, sc[1][0][1]), sc[1][0][2]); am = fmaxf(am, sc[1][0][3]);
; #pragma unroll
;             for (int qb = 1; qb < NQ; ++qb) { am = fmaxf(fmaxf(am, sc[0][qb][0]), sc[0][qb][1]); am = fmaxf(fmaxf(am, sc[0][qb][2]), sc[0][qb][3]);
;                 am = fmaxf(fmaxf(am, sc[1][qb][0]), sc[1][qb][1]); am = fmaxf(fmaxf(am, sc[1][qb][2]), sc[1][qb][3]); }
;             if (__any(first || (am > ATT_THR))) {
; #pragma unroll
;                 for (int qb = 0; qb < NQ; ++qb) {
;                     float a = fmaxf(fmaxf(sc[0][qb][0], sc[0][qb][1]), sc[0][qb][2]);
;                     a = fmaxf(fmaxf(a, sc[0][qb][3]), sc[1][qb][0]); a = fmaxf(fmaxf(a, sc[1][qb][1]), sc[1][qb][2]); a = fmaxf(a, sc[1][qb][3]);
;                     { auto r16 = __builtin_amdgcn_permlane16_swap(__float_as_uint(a), __float_as_uint(a), false, false); a = fmaxf(__uint_as_float(r16[0]), __uint_as_float(r16[1])); }
.Lmla_common_a:
	s_waitcnt lgkmcnt(5)
	v_mfma_f32_16x16x32_bf16 v[216:219], v[232:235], v[92:95], v[160:163]
	v_exp_f32_e32 v180, v180
	v_exp_f32_e32 v181, v181
	v_exp_f32_e32 v182, v182
	v_mfma_f32_16x16x32_bf16 v[220:223], v[232:235], v[104:107], v[156:159]
	v_exp_f32_e32 v183, v183
	v_exp_f32_e32 v196, v196
	v_exp_f32_e32 v197, v197
	v_mfma_f32_16x16x32_bf16 v[224:227], v[232:235], v[116:119], v[152:155]
	v_exp_f32_e32 v198, v198
	v_exp_f32_e32 v199, v199
	v_cvt_pk_bf16_f32 v180, v180, v181
	v_mfma_f32_16x16x32_bf16 v[228:231], v[232:235], v[128:131], v[164:167]
	v_cvt_pk_bf16_f32 v181, v182, v183
	v_cvt_pk_bf16_f32 v182, v196, v197
	v_cvt_pk_bf16_f32 v183, v198, v199
	s_waitcnt lgkmcnt(4)
	v_mfma_f32_16x16x32_bf16 v[216:219], v[44:47], v[96:99], v[216:219]
	v_exp_f32_e32 v176, v176
	v_exp_f32_e32 v177, v177
	v_exp_f32_e32 v178, v178
	v_mfma_f32_16x16x32_bf16 v[220:223], v[44:47], v[108:111], v[220:223]
	v_exp_f32_e32 v179, v179
	v_exp_f32_e32 v192, v192
	v_exp_f32_e32 v193, v193
	v_mfma_f32_16x16x32_bf16 v[224:227], v[44:47], v[120:123], v[224:227]
	v_exp_f32_e32 v194, v194
	v_exp_f32_e32 v195, v195
	v_cvt_pk_bf16_f32 v176, v176, v177
	v_mfma_f32_16x16x32_bf16 v[228:231], v[44:47], v[132:135], v[228:231]
	v_cvt_pk_bf16_f32 v177, v178, v179
	v_cvt_pk_bf16_f32 v178, v192, v193
	v_cvt_pk_bf16_f32 v179, v194, v195
	s_waitcnt lgkmcnt(3)
	v_mfma_f32_16x16x32_bf16 v[216:219], v[200:203], v[100:103], v[216:219]
	v_exp_f32_e32 v172, v172
	v_exp_f32_e32 v173, v173
	v_exp_f32_e32 v174, v174
	v_mfma_f32_16x16x32_bf16 v[220:223], v[200:203], v[112:115], v[220:223]
	v_exp_f32_e32 v175, v175
	v_exp_f32_e32 v188, v188
	v_exp_f32_e32 v189, v189
	v_mfma_f32_16x16x32_bf16 v[224:227], v[200:203], v[124:127], v[224:227]
	v_exp_f32_e32 v190, v190
	v_exp_f32_e32 v191, v191
	v_cvt_pk_bf16_f32 v172, v172, v173
	v_mfma_f32_16x16x32_bf16 v[228:231], v[200:203], v[136:139], v[228:231]
	v_cvt_pk_bf16_f32 v173, v174, v175
	v_cvt_pk_bf16_f32 v174, v188, v189
	v_cvt_pk_bf16_f32 v175, v190, v191
	s_waitcnt lgkmcnt(2)
	v_mfma_f32_16x16x32_bf16 v[232:235], v[236:239], v[92:95], v[160:163]
	v_exp_f32_e32 v168, v168
	v_exp_f32_e32 v169, v169
	v_exp_f32_e32 v170, v170
	v_mfma_f32_16x16x32_bf16 v[44:47], v[236:239], v[104:107], v[156:159]
	v_exp_f32_e32 v171, v171
	v_exp_f32_e32 v184, v184
	v_exp_f32_e32 v185, v185
	v_mfma_f32_16x16x32_bf16 v[200:203], v[236:239], v[116:119], v[152:155]
	v_exp_f32_e32 v186, v186
	v_exp_f32_e32 v187, v187
	v_cvt_pk_bf16_f32 v168, v168, v169
	v_mfma_f32_16x16x32_bf16 v[236:239], v[236:239], v[128:131], v[164:167]
	v_cvt_pk_bf16_f32 v169, v170, v171
	v_cvt_pk_bf16_f32 v170, v184, v185
	v_cvt_pk_bf16_f32 v171, v186, v187
	ds_read_b128 v[196:199], v38 offset:24576
	ds_read_b128 v[192:195], v38 offset:26880
	ds_read_b128 v[188:191], v38 offset:29184
	ds_read_b128 v[184:187], v38 offset:31488
	s_waitcnt lgkmcnt(5)
	v_mfma_f32_16x16x32_bf16 v[232:235], v[242:245], v[96:99], v[232:235]
	v_mfma_f32_16x16x32_bf16 v[44:47], v[242:245], v[108:111], v[44:47]
	v_mfma_f32_16x16x32_bf16 v[200:203], v[242:245], v[120:123], v[200:203]
	v_mfma_f32_16x16x32_bf16 v[236:239], v[242:245], v[132:135], v[236:239]
	s_waitcnt lgkmcnt(4)
	v_mfma_f32_16x16x32_bf16 v[232:235], v[246:249], v[100:103], v[232:235]
	v_mfma_f32_16x16x32_bf16 v[44:47], v[246:249], v[112:115], v[44:47]
	v_mfma_f32_16x16x32_bf16 v[200:203], v[246:249], v[124:127], v[200:203]
	v_mfma_f32_16x16x32_bf16 v[236:239], v[246:249], v[136:139], v[236:239]
	v_mov_b32_e32 v246, s12
	v_mov_b32_e32 v247, s12
	v_mov_b32_e32 v248, s12
	v_mov_b32_e32 v249, s12
	s_waitcnt lgkmcnt(3)
	v_mfma_f32_16x16x32_bf16 v[76:79], v[196:199], v[180:183], v[76:79]
	v_max_f32_e32 v242, v216, v217
	v_mfma_f32_16x16x32_bf16 v[56:59], v[196:199], v[176:179], v[56:59]
	v_max_f32_e32 v243, v220, v221
	v_mfma_f32_16x16x32_bf16 v[24:27], v[196:199], v[172:175], v[24:27]
	v_max_f32_e32 v244, v224, v225
	v_mfma_f32_16x16x32_bf16 v[4:7], v[196:199], v[168:171], v[4:7]
	ds_read_b128 v[196:199], v38 offset:24640
	v_max_f32_e32 v245, v228, v229
	s_waitcnt lgkmcnt(3)
	v_mfma_f32_16x16x32_bf16 v[80:83], v[192:195], v[180:183], v[80:83]
	v_max3_f32 v242, v242, v218, v219
	v_mfma_f32_16x16x32_bf16 v[60:63], v[192:195], v[176:179], v[60:63]
	v_max3_f32 v243, v243, v222, v223
	v_mfma_f32_16x16x32_bf16 v[28:31], v[192:195], v[172:175], v[28:31]
	v_max3_f32 v244, v244, v226, v227
	v_mfma_f32_16x16x32_bf16 v[8:11], v[192:195], v[168:171], v[8:11]
	ds_read_b128 v[192:195], v38 offset:26944
	v_max3_f32 v245, v245, v230, v231
	s_waitcnt lgkmcnt(3)
	v_mfma_f32_16x16x32_bf16 v[84:87], v[188:191], v[180:183], v[84:87]
	v_max3_f32 v242, v242, v232, v233
	v_mfma_f32_16x16x32_bf16 v[64:67], v[188:191], v[176:179], v[64:67]
	v_max3_f32 v243, v243, v44, v45
	v_mfma_f32_16x16x32_bf16 v[32:35], v[188:191], v[172:175], v[32:35]
	v_max3_f32 v244, v244, v200, v201
	v_mfma_f32_16x16x32_bf16 v[12:15], v[188:191], v[168:171], v[12:15]
	ds_read_b128 v[188:191], v38 offset:29248
	v_max3_f32 v245, v245, v236, v237
	s_waitcnt lgkmcnt(3)
	v_mfma_f32_16x16x32_bf16 v[72:75], v[184:187], v[180:183], v[72:75]
	v_max3_f32 v242, v242, v234, v235
	v_mfma_f32_16x16x32_bf16 v[52:55], v[184:187], v[176:179], v[52:55]
	v_max3_f32 v243, v243, v46, v47
	v_mfma_f32_16x16x32_bf16 v[20:23], v[184:187], v[172:175], v[20:23]
	v_max3_f32 v244, v244, v202, v203
	v_mfma_f32_16x16x32_bf16 v[0:3], v[184:187], v[168:171], v[0:3]
	ds_read_b128 v[184:187], v38 offset:31552
	v_max3_f32 v245, v245, v238, v239
	v_mfma_f32_16x16x32_bf16 v[88:91], v[246:249], v[180:183], v[88:91]
	v_max3_f32 v39, v242, v243, v244
	v_mfma_f32_16x16x32_bf16 v[68:71], v[246:249], v[176:179], v[68:71]
	v_max_f32_e32 v39, v39, v245
	v_mfma_f32_16x16x32_bf16 v[48:51], v[246:249], v[172:175], v[48:51]
	v_mfma_f32_16x16x32_bf16 v[16:19], v[246:249], v[168:171], v[16:19]
	v_cmp_lt_f32_e32 vcc, 4.0, v39
	s_or_b64 s[0:1], s[10:11], vcc
	s_cmp_lg_u64 s[0:1], 0
	s_cbranch_scc1 .Lmla_rare_b
; __device__ __forceinline__ unsigned pk2(float lo, float hi) { f32x2_t v = {lo, hi}; bf16x2_t b = __builtin_convertvector(v, bf16x2_t); return __builtin_bit_cast(unsigned, b); }
; template <int DQK, bool MASK, int NQ>
; __device__ __forceinline__ void attn_unit(unsigned char* lds, const bf16_t* Qg, int ldq, const bf16_t* Kg, int ldk, const bf16_t* Vtg, bf16_t* Og, int ldo,
;                                           int qi0, int a0, int n1, int b0, int n2, float m0, bool sink) {
;     ...
;             bf16x8 pf[NQ];
; #pragma unroll
;             for (int qb = 0; qb < NQ; ++qb) {
; #pragma unroll
;                 for (int k2 = 0; k2 < 2; ++k2)
; #pragma unroll
;                     for (int j = 0; j < 4; ++j) sc[k2][qb][j] = __builtin_amdgcn_exp2f(sc[k2][qb][j]);
;                 u32x4 w; w.x = pk2(sc[0][qb][0], sc[0][qb][1]); w.y = pk2(sc[0][qb][2], sc[0][qb][3]); w.z = pk2(sc[1][qb][0], sc[1][qb][1]); w.w = pk2(sc[1][qb][2], sc[1][qb][3]);
;                 pf[qb] = __builtin_bit_cast(bf16x8, w); }
;             { const unsigned char* vb_ = lds + VOFF + (tt & 1) * VBYTES + (hb * 4 + g) * 16;
; #pragma unroll
;               for (int eb = 0; eb < 4; ++eb) {
;                   const bf16x8 vf = *(const bf16x8*)(vb_ + (eb * 16 + ql) * (VP * 2));
; #pragma unroll
;                   for (int qb = 0; qb < NQ; ++qb) o[eb][qb] = __builtin_amdgcn_mfma_f32_16x16x32_bf16(vf, pf[qb], o[eb][qb], 0, 0, 0);
;               }
; #pragma unroll
;               for (int qb = 0; qb < NQ; ++qb) ol[qb] = __builtin_amdgcn_mfma_f32_16x16x32_bf16(ones, pf[qb], ol[qb], 0, 0, 0); }
;           }
;         }
;         if (tt + 1 < nt) ATT_COMMIT((tt + 1) & 1);
.Lmla_common_b:
	v_exp_f32_e32 v216, v216
	v_exp_f32_e32 v217, v217
	v_exp_f32_e32 v218, v218
	v_exp_f32_e32 v219, v219
	v_exp_f32_e32 v232, v232
	v_exp_f32_e32 v233, v233
	v_exp_f32_e32 v234, v234
	v_exp_f32_e32 v235, v235
	v_cvt_pk_bf16_f32 v216, v216, v217
	v_cvt_pk_bf16_f32 v217, v218, v219
	v_cvt_pk_bf16_f32 v218, v232, v233
	v_cvt_pk_bf16_f32 v219, v234, v235
	s_nop 1
	s_waitcnt lgkmcnt(3)
	v_mfma_f32_16x16x32_bf16 v[76:79], v[196:199], v[216:219], v[76:79]
	v_exp_f32_e32 v220, v220
	v_exp_f32_e32 v221, v221
	v_exp_f32_e32 v222, v222
	s_waitcnt lgkmcnt(2)
	v_mfma_f32_16x16x32_bf16 v[80:83], v[192:195], v[216:219], v[80:83]
	v_exp_f32_e32 v223, v223
	v_exp_f32_e32 v44, v44
	v_exp_f32_e32 v45, v45
	s_waitcnt lgkmcnt(1)
	v_mfma_f32_16x16x32_bf16 v[84:87], v[188:191], v[216:219], v[84:87]
	v_exp_f32_e32 v46, v46
	v_exp_f32_e32 v47, v47
	v_cvt_pk_bf16_f32 v220, v220, v221
	s_waitcnt lgkmcnt(0)
	v_mfma_f32_16x16x32_bf16 v[72:75], v[184:187], v[216:219], v[72:75]
	v_cvt_pk_bf16_f32 v221, v222, v223
	v_cvt_pk_bf16_f32 v222, v44, v45
	v_cvt_pk_bf16_f32 v223, v46, v47
	v_mfma_f32_16x16x32_bf16 v[88:91], v[246:249], v[216:219], v[88:91]
	v_mfma_f32_16x16x32_bf16 v[56:59], v[196:199], v[220:223], v[56:59]
	v_exp_f32_e32 v224, v224
	v_exp_f32_e32 v225, v225
	v_exp_f32_e32 v226, v226
	v_mfma_f32_16x16x32_bf16 v[60:63], v[192:195], v[220:223], v[60:63]
	v_exp_f32_e32 v227, v227
	v_exp_f32_e32 v200, v200
	v_exp_f32_e32 v201, v201
	v_mfma_f32_16x16x32_bf16 v[64:67], v[188:191], v[220:223], v[64:67]
	v_exp_f32_e32 v202, v202
	v_exp_f32_e32 v203, v203
	v_cvt_pk_bf16_f32 v224, v224, v225
	v_mfma_f32_16x16x32_bf16 v[52:55], v[184:187], v[220:223], v[52:55]
	v_cvt_pk_bf16_f32 v225, v226, v227
	v_cvt_pk_bf16_f32 v226, v200, v201
	v_cvt_pk_bf16_f32 v227, v202, v203
	v_mfma_f32_16x16x32_bf16 v[68:71], v[246:249], v[220:223], v[68:71]
	v_mfma_f32_16x16x32_bf16 v[24:27], v[196:199], v[224:227], v[24:27]
	v_exp_f32_e32 v228, v228
	v_exp_f32_e32 v229, v229
	v_exp_f32_e32 v230, v230
	v_mfma_f32_16x16x32_bf16 v[28:31], v[192:195], v[224:227], v[28:31]
	v_exp_f32_e32 v231, v231
	v_exp_f32_e32 v236, v236
	v_exp_f32_e32 v237, v237
	v_mfma_f32_16x16x32_bf16 v[32:35], v[188:191], v[224:227], v[32:35]
	v_exp_f32_e32 v238, v238
	v_exp_f32_e32 v239, v239
	v_cvt_pk_bf16_f32 v228, v228, v229
	v_mfma_f32_16x16x32_bf16 v[20:23], v[184:187], v[224:227], v[20:23]
	v_cvt_pk_bf16_f32 v229, v230, v231
	v_cvt_pk_bf16_f32 v230, v236, v237
	v_cvt_pk_bf16_f32 v231, v238, v239
	v_mfma_f32_16x16x32_bf16 v[48:51], v[246:249], v[224:227], v[48:51]
	v_mfma_f32_16x16x32_bf16 v[4:7], v[196:199], v[228:231], v[4:7]
	v_mfma_f32_16x16x32_bf16 v[8:11], v[192:195], v[228:231], v[8:11]
	v_mfma_f32_16x16x32_bf16 v[12:15], v[188:191], v[228:231], v[12:15]
	v_mfma_f32_16x16x32_bf16 v[0:3], v[184:187], v[228:231], v[0:3]
	v_mfma_f32_16x16x32_bf16 v[16:19], v[246:249], v[228:231], v[16:19]
	s_cmp_ge_i32 s24, s19
	s_cbranch_scc1 .Lmla_nocommit
	s_and_b32 s0, s24, 1
	s_mul_i32 s1, s0, 0x3000
	v_add_u32_e32 v37, s1, v205
	s_waitcnt vmcnt(1)
	ds_write_b128 v37, v[140:143]
	s_and_saveexec_b64 s[14:15], s[38:39]
	ds_write_b128 v37, v[144:147] offset:8192
	s_or_b64 exec, exec, s[14:15]
	s_mulk_i32 s0, 0x2400
	v_add_u32_e32 v37, s0, v209
	v_add_u32_e32 v37, 0x6000, v37
	s_waitcnt vmcnt(0)
	ds_write2_b64 v37, v[148:149], v[150:151] offset1:2

; template <int DQK, bool MASK, int NQ>
; __device__ __forceinline__ void attn_unit(unsigned char* lds, const bf16_t* Qg, int ldq, const bf16_t* Kg, int ldk, const bf16_t* Vtg, bf16_t* Og, int ldo,
;                                           int qi0, int a0, int n1, int b0, int n2, float m0, bool sink) {
;     ...
;             if (__any(first || (am > ATT_THR))) {
; #pragma unroll
;                 for (int qb = 0; qb < NQ; ++qb) {
;                     float a = fmaxf(fmaxf(sc[0][qb][0], sc[0][qb][1]), sc[0][qb][2]);
;                     a = fmaxf(fmaxf(a, sc[0][qb][3]), sc[1][qb][0]); a = fmaxf(fmaxf(a, sc[1][qb][1]), sc[1][qb][2]); a = fmaxf(a, sc[1][qb][3]);
;                     { auto r16 = __builtin_amdgcn_permlane16_swap(__float_as_uint(a), __float_as_uint(a), false, false); a = fmaxf(__uint_as_float(r16[0]), __uint_as_float(r16[1])); }
;                     { auto r32 = __builtin_amdgcn_permlane32_swap(__float_as_uint(a), __float_as_uint(a), false, false); a = fmaxf(__uint_as_float(r32[0]), __uint_as_float(r32[1])); }
;                     const float dlt = first ? a : fmaxf(a, 0.f);
;                     mrow[qb] += dlt; negm[qb] = (f32x4){-mrow[qb], -mrow[qb], -mrow[qb], -mrow[qb]};
;                     sc[0][qb] = sc[0][qb] - dlt; sc[1][qb] = sc[1][qb] - dlt;
;                     if (!first) { const float alpha = __builtin_amdgcn_exp2f(-dlt); ol[qb] = ol[qb] * alpha;
; #pragma unroll
;                         for (int eb = 0; eb < 4; ++eb) o[eb][qb] = o[eb][qb] * alpha; } }
;                 first = false; }
.Lmla_rare_b:
	s_nop 7
	v_mov_b32_e32 v39, v242
	s_nop 1
	v_permlane16_swap_b32_e32 v242, v39
	v_max_f32_e32 v39, v39, v39
	v_max_f32_e32 v242, v242, v242
	v_max_f32_e32 v242, v242, v39
	v_mov_b32_e32 v39, v242
	s_nop 1
	v_permlane32_swap_b32_e32 v242, v39
	v_max_f32_e32 v39, v39, v39
	v_max_f32_e32 v242, v242, v242
	v_max_f32_e32 v242, v242, v39
	v_max_f32_e32 v180, 0, v242
	v_mov_b32_e32 v39, v243
	s_nop 1
	v_permlane16_swap_b32_e32 v243, v39
	v_max_f32_e32 v39, v39, v39
	v_max_f32_e32 v243, v243, v243
	v_max_f32_e32 v243, v243, v39
	v_mov_b32_e32 v39, v243
	s_nop 1
	v_permlane32_swap_b32_e32 v243, v39
	v_max_f32_e32 v39, v39, v39
	v_max_f32_e32 v243, v243, v243
	v_max_f32_e32 v243, v243, v39
	v_max_f32_e32 v181, 0, v243
	v_mov_b32_e32 v39, v244
	s_nop 1
	v_permlane16_swap_b32_e32 v244, v39
	v_max_f32_e32 v39, v39, v39
	v_max_f32_e32 v244, v244, v244
	v_max_f32_e32 v244, v244, v39
	v_mov_b32_e32 v39, v244
	s_nop 1
	v_permlane32_swap_b32_e32 v244, v39
	v_max_f32_e32 v39, v39, v39
	v_max_f32_e32 v244, v244, v244
	v_max_f32_e32 v244, v244, v39
	v_max_f32_e32 v182, 0, v244
	v_mov_b32_e32 v39, v245
	s_nop 1
	v_permlane16_swap_b32_e32 v245, v39
	v_max_f32_e32 v39, v39, v39
	v_max_f32_e32 v245, v245, v245
	v_max_f32_e32 v245, v245, v39
	v_mov_b32_e32 v39, v245
	s_nop 1
	v_permlane32_swap_b32_e32 v245, v39
	v_max_f32_e32 v39, v39, v39
	v_max_f32_e32 v245, v245, v245
	v_max_f32_e32 v245, v245, v39
	v_max_f32_e32 v183, 0, v245
	s_cmp_lg_u64 s[10:11], 0
	s_cbranch_scc1 .Lmla_rare_b_ns
	v_exp_f32_e64 v168, -v180
	v_exp_f32_e64 v170, -v181
	v_exp_f32_e64 v172, -v182
	v_exp_f32_e64 v174, -v183
	s_nop 0
	v_pk_mul_f32 v[88:89], v[88:89], v[168:169] op_sel_hi:[1,0]
	v_pk_mul_f32 v[90:91], v[90:91], v[168:169] op_sel_hi:[1,0]
	v_pk_mul_f32 v[76:77], v[76:77], v[168:169] op_sel_hi:[1,0]
	v_pk_mul_f32 v[78:79], v[78:79], v[168:169] op_sel_hi:[1,0]
	v_pk_mul_f32 v[80:81], v[80:81], v[168:169] op_sel_hi:[1,0]
	v_pk_mul_f32 v[82:83], v[82:83], v[168:169] op_sel_hi:[1,0]
	v_pk_mul_f32 v[84:85], v[84:85], v[168:169] op_sel_hi:[1,0]
	v_pk_mul_f32 v[86:87], v[86:87], v[168:169] op_sel_hi:[1,0]
	v_pk_mul_f32 v[72:73], v[72:73], v[168:169] op_sel_hi:[1,0]
	v_pk_mul_f32 v[74:75], v[74:75], v[168:169] op_sel_hi:[1,0]
	v_pk_mul_f32 v[68:69], v[68:69], v[170:171] op_sel_hi:[1,0]
	v_pk_mul_f32 v[70:71], v[70:71], v[170:171] op_sel_hi:[1,0]
	v_pk_mul_f32 v[56:57], v[56:57], v[170:171] op_sel_hi:[1,0]
	v_pk_mul_f32 v[58:59], v[58:59], v[170:171] op_sel_hi:[1,0]
	v_pk_mul_f32 v[60:61], v[60:61], v[170:171] op_sel_hi:[1,0]
	v_pk_mul_f32 v[62:63], v[62:63], v[170:171] op_sel_hi:[1,0]
	v_pk_mul_f32 v[64:65], v[64:65], v[170:171] op_sel_hi:[1,0]
	v_pk_mul_f32 v[66:67], v[66:67], v[170:171] op_sel_hi:[1,0]
	v_pk_mul_f32 v[52:53], v[52:53], v[170:171] op_sel_hi:[1,0]
	v_pk_mul_f32 v[54:55], v[54:55], v[170:171] op_sel_hi:[1,0]
	v_pk_mul_f32 v[48:49], v[48:49], v[172:173] op_sel_hi:[1,0]
	v_pk_mul_f32 v[50:51], v[50:51], v[172:173] op_sel_hi:[1,0]
	v_pk_mul_f32 v[24:25], v[24:25], v[172:173] op_sel_hi:[1,0]
	v_pk_mul_f32 v[26:27], v[26:27], v[172:173] op_sel_hi:[1,0]
	v_pk_mul_f32 v[28:29], v[28:29], v[172:173] op_sel_hi:[1,0]
	v_pk_mul_f32 v[30:31], v[30:31], v[172:173] op_sel_hi:[1,0]
	v_pk_mul_f32 v[32:33], v[32:33], v[172:173] op_sel_hi:[1,0]
	v_pk_mul_f32 v[34:35], v[34:35], v[172:173] op_sel_hi:[1,0]
	v_pk_mul_f32 v[20:21], v[20:21], v[172:173] op_sel_hi:[1,0]
	v_pk_mul_f32 v[22:23], v[22:23], v[172:173] op_sel_hi:[1,0]
	v_pk_mul_f32 v[16:17], v[16:17], v[174:175] op_sel_hi:[1,0]
	v_pk_mul_f32 v[18:19], v[18:19], v[174:175] op_sel_hi:[1,0]
	v_pk_mul_f32 v[4:5], v[4:5], v[174:175] op_sel_hi:[1,0]
	v_pk_mul_f32 v[6:7], v[6:7], v[174:175] op_sel_hi:[1,0]
	v_pk_mul_f32 v[8:9], v[8:9], v[174:175] op_sel_hi:[1,0]
	v_pk_mul_f32 v[10:11], v[10:11], v[174:175] op_sel_hi:[1,0]
	v_pk_mul_f32 v[12:13], v[12:13], v[174:175] op_sel_hi:[1,0]
	v_pk_mul_f32 v[14:15], v[14:15], v[174:175] op_sel_hi:[1,0]
	v_pk_mul_f32 v[0:1], v[0:1], v[174:175] op_sel_hi:[1,0]
	v_pk_mul_f32 v[2:3], v[2:3], v[174:175] op_sel_hi:[1,0]
